# MLA loop as matrix block (PV then next QK) and vector block (softmax + DMA issue), barriers at both boundaries, waves 4-7 one barrier behind waves 0-3
# speedup vs baseline: 1.0252x; 1.0104x over previous
; #define MLA_DMA(t, slot) do { _Pragma("unroll") for (int i_ = 0; i_ < 4; ++i_) { const bf16_t* src_ = (pisk[i_] ? kbase : vbase) + poff[i_] + (size_t)(t) * pstep[i_]; \
;         __builtin_amdgcn_global_load_lds((const unsigned*)src_, (LAS unsigned*)(lds + (slot) * SLOT + (w + 8 * i_) * 1024), 16, 0, 0); } } while (0)
; DI void mla_attn_phase(LAS unsigned char* lds, const bf16_t* Qg, const bf16_t* Kg, const bf16_t* Vtg, bf16_t* MIX) {
;     ...
;             const int qb = half ? pi : 63 - pi, q0 = qb * 256 + 32 * w, NT = 4 * (qb + 1);
;     ...
;             const bf16_t* qp = Qg + ((size_t)bh * SEQ + q0 + r32) * 96 + 8 * hf;
;             bf16x8 qf[6];
; #pragma unroll
;             for (int ks = 0; ks < 6; ++ks) qf[ks] = *(const bf16x8*)(qp + 16 * ks);
;             asm volatile("" ::: "memory");
;             MLA_DMA(0, 0); MLA_DMA(1, 1);
;             f32x16 o[4];
; #pragma unroll
;             for (int mt = 0; mt < 4; ++mt)
; #pragma unroll
;                 for (int i = 0; i < 16; ++i) o[mt][i] = 0.f;
;             float m_run = -1e30f, l_run = 0.f;
;     ...
;             asm volatile("s_waitcnt vmcnt(4)" ::: "memory");
;             __builtin_amdgcn_s_barrier(); asm volatile("" ::: "memory");
;             int sl = 0;
;     ...
;                 const int sl2 = sl == 0 ? 2 : sl - 1;
;                 if (kt + 2 < NT) MLA_DMA(kt + 2, sl2);
.LBB0_357:
	s_and_b64 s[26:27], s[24:25], exec
	s_cselect_b32 s8, s37, s36
	s_lshl_b32 s26, s8, 8
	s_add_i32 s26, s26, s34
	s_ashr_i32 s27, s26, 31
	v_lshl_add_u64 v[0:1], v[180:181], 0, s[26:27]
	s_movk_i32 s30, 0xc0
	s_waitcnt lgkmcnt(0)
	v_mad_u64_u32 v[4:5], s[28:29], v0, s30, v[168:169]
	v_mad_i32_i24 v5, v1, s30, v5
	s_mov_b32 m0, s35
	global_load_dwordx4 v[112:115], v[4:5], off
	global_load_dwordx4 v[116:119], v[4:5], off offset:32
	global_load_dwordx4 v[120:123], v[4:5], off offset:64
	global_load_dwordx4 v[124:127], v[4:5], off offset:96
	global_load_dwordx4 v[128:131], v[4:5], off offset:128
	global_load_dwordx4 v[132:135], v[4:5], off offset:160
	global_load_lds_dwordx4 v[184:185], off
	s_add_i32 m0, s35, 0x2000
	s_nop 0
	global_load_lds_dwordx4 v[186:187], off
	s_add_i32 m0, s35, 0x4000
	s_nop 0
	global_load_lds_dwordx4 v[188:189], off
	s_add_i32 m0, s35, 0x6000
	s_nop 0
	global_load_lds_dwordx4 v[190:191], off
	s_add_i32 m0, s35, 0x8000
	s_nop 0
	global_load_lds_dwordx4 v[192:193], off
	s_add_i32 m0, s35, 0xa000
	s_nop 0
	global_load_lds_dwordx4 v[194:195], off
	s_add_i32 m0, s35, 0xc000
	s_nop 0
	global_load_lds_dwordx4 v[196:197], off
	s_add_i32 m0, s35, 0xe000
	s_cmp_lt_i32 s8, 0
	global_load_lds_dwordx4 v[198:199], off
	s_waitcnt vmcnt(4)
	s_barrier
	s_cbranch_scc1 .LBB0_355
	s_waitcnt lgkmcnt(0)
	v_mov_b32_e32 v14, v2
	v_mov_b32_e32 v15, v2
	s_lshl_b32 s8, s8, 2
	v_mov_b32_e32 v0, v2
	v_mov_b32_e32 v1, v2
	v_mov_b32_e32 v3, v2
	v_mov_b32_e32 v4, v2
	v_mov_b32_e32 v5, v2
	v_mov_b32_e32 v6, v2
	v_mov_b32_e32 v7, v2
	v_mov_b32_e32 v8, v2
	v_mov_b32_e32 v9, v2
	v_mov_b32_e32 v10, v2
	v_mov_b32_e32 v11, v2
	v_mov_b32_e32 v12, v2
	v_mov_b32_e32 v13, v2
	v_mov_b64_e32 v[30:31], v[14:15]
	v_mov_b64_e32 v[46:47], v[14:15]
	v_mov_b64_e32 v[62:63], v[14:15]
	v_mov_b64_e32 v[78:79], v[14:15]
	s_add_i32 s38, s8, 4
	s_or_b32 s39, s26, 31
	v_or_b32_e32 v167, s26, v164
	s_mov_b32 s40, 0
	v_mov_b32_e32 v234, 0xf149f2ca
	v_mov_b32_e32 v233, 0
	v_mov_b64_e32 v[210:211], v[208:209]
	v_mov_b64_e32 v[212:213], v[206:207]
	v_mov_b64_e32 v[214:215], v[204:205]
	v_mov_b64_e32 v[216:217], v[202:203]
	v_mov_b64_e32 v[28:29], v[12:13]
	v_mov_b64_e32 v[26:27], v[10:11]
	v_mov_b64_e32 v[24:25], v[8:9]
	v_mov_b64_e32 v[22:23], v[6:7]
	v_mov_b64_e32 v[20:21], v[4:5]
	v_mov_b64_e32 v[18:19], v[2:3]
	v_mov_b64_e32 v[16:17], v[0:1]
	v_mov_b64_e32 v[44:45], v[12:13]
	v_mov_b64_e32 v[42:43], v[10:11]
	v_mov_b64_e32 v[40:41], v[8:9]
	v_mov_b64_e32 v[38:39], v[6:7]
	v_mov_b64_e32 v[36:37], v[4:5]
	v_mov_b64_e32 v[34:35], v[2:3]
	v_mov_b64_e32 v[32:33], v[0:1]
	v_mov_b64_e32 v[60:61], v[12:13]
	v_mov_b64_e32 v[58:59], v[10:11]
	v_mov_b64_e32 v[56:57], v[8:9]
	v_mov_b64_e32 v[54:55], v[6:7]
	v_mov_b64_e32 v[52:53], v[4:5]
	v_mov_b64_e32 v[50:51], v[2:3]
	v_mov_b64_e32 v[48:49], v[0:1]
	v_mov_b64_e32 v[76:77], v[12:13]
	v_mov_b64_e32 v[74:75], v[10:11]
	v_mov_b64_e32 v[72:73], v[8:9]
	v_mov_b64_e32 v[70:71], v[6:7]
	v_mov_b64_e32 v[68:69], v[4:5]
	v_mov_b64_e32 v[66:67], v[2:3]
	v_mov_b64_e32 v[64:65], v[0:1]
	s_mov_b32 s41, 0
	s_mov_b32 s42, 0
	s_waitcnt vmcnt(0)
	s_cmp_lt_u32 s34, 0x80
	s_cbranch_scc1 .Lmla_pro_done
	s_add_i32 s31, s35, 0x10000
	s_mov_b32 m0, s31
	s_nop 0
	global_load_lds_dwordx4 v[210:211], off
	s_add_i32 m0, s31, 0x2000
	s_nop 0
	global_load_lds_dwordx4 v[212:213], off
	s_add_i32 m0, s31, 0x4000
	s_nop 0
	global_load_lds_dwordx4 v[214:215], off
	s_add_i32 m0, s31, 0x6000
	s_nop 0
	global_load_lds_dwordx4 v[216:217], off
	v_lshl_add_u64 v[216:217], v[216:217], 0, s[18:19]
	v_lshl_add_u64 v[214:215], v[214:215], 0, s[20:21]
	v_lshl_add_u64 v[212:213], v[212:213], 0, s[2:3]
	v_lshl_add_u64 v[210:211], v[210:211], 0, s[22:23]
	s_barrier
.Lmla_pro_done:
.LBB0_359:
	s_cmp_lt_u32 s34, 0x80
	s_cselect_b32 s30, 2, 3
	s_add_i32 s28, s42, s30
	s_add_i32 s31, s41, s30
	s_cmp_ge_i32 s28, s38
	s_cselect_b64 s[28:29], -1, 0
	s_and_b32 s31, s31, 3
	s_lshl_b32 s31, s31, 15
	s_add_i32 s31, s35, s31

; DI void mla_attn_phase(LAS unsigned char* lds, const bf16_t* Qg, const bf16_t* Kg, const bf16_t* Vtg, bf16_t* MIX) {
;     ...
;                 if (kt + 2 < NT) asm volatile("s_waitcnt vmcnt(4) lgkmcnt(0)" ::: "memory"); else asm volatile("s_waitcnt vmcnt(0) lgkmcnt(0)" ::: "memory");
;                 __builtin_amdgcn_s_barrier(); asm volatile("" ::: "memory");
.Lmla_z:
	s_cmp_lt_u32 s34, 0x80
	s_cbranch_scc1 .Lmla_zb
	s_add_i32 s30, s42, 2
	s_cmp_ge_i32 s30, s38
	s_cbranch_scc1 .Lmla_zw0
	s_waitcnt vmcnt(4)
	s_branch .Lmla_zb

; DI int crow(int r, int hi) { return (r & 3) + 8 * (r >> 2) + 4 * hi; }
; DI void mla_attn_phase(LAS unsigned char* lds, const bf16_t* Qg, const bf16_t* Kg, const bf16_t* Vtg, bf16_t* MIX) {
;     ...
;                     if (kt >= 4 * qb) { const int qpos = q0 + r32;
; #pragma unroll
;                         for (int i = 0; i < 16; ++i) { const int key0 = 64 * kt + crow(i, hf); if (key0 > qpos) s0[i] = -INFINITY; if (key0 + 32 > qpos) s1[i] = -INFINITY; } }
.Lmla_zb:
	s_barrier
	s_cmp_gt_i32 s40, s39
	s_cbranch_scc1 .Lmla_dma
	s_cmp_lt_i32 s42, s8
	s_cbranch_scc1 .LBB0_364
	v_add_u32_e32 v0, s40, v231
	v_add_u32_e32 v3, 32, v0
	v_cmp_le_i32_e32 vcc, v3, v167
	v_add_u32_e32 v3, 33, v0
	s_nop 5
	v_cndmask_b32_e32 v96, v229, v96, vcc
	v_cmp_lt_i32_e32 vcc, v0, v167
	s_nop 1
	v_cndmask_b32_e32 v81, v229, v81, vcc
	v_cmp_le_i32_e32 vcc, v0, v167
	s_nop 1
	v_cndmask_b32_e32 v80, v229, v80, vcc
	v_cmp_le_i32_e32 vcc, v3, v167
	v_add_u32_e32 v3, 2, v0
	s_nop 0
	v_cndmask_b32_e32 v97, v229, v97, vcc
	v_cmp_le_i32_e32 vcc, v3, v167
	v_add_u32_e32 v3, 34, v0
	s_nop 0
	v_cndmask_b32_e32 v82, v229, v82, vcc
	v_cmp_le_i32_e32 vcc, v3, v167
	v_add_u32_e32 v3, 3, v0
	s_nop 0
	v_cndmask_b32_e32 v98, v229, v98, vcc
	v_cmp_le_i32_e32 vcc, v3, v167
	v_add_u32_e32 v3, 35, v0
	s_nop 0
	v_cndmask_b32_e32 v83, v229, v83, vcc
	v_cmp_le_i32_e32 vcc, v3, v167
	v_add_u32_e32 v3, 8, v0
	s_nop 0
	v_cndmask_b32_e32 v99, v229, v99, vcc
	v_cmp_le_i32_e32 vcc, v3, v167
	v_add_u32_e32 v3, 40, v0
	s_nop 0
	v_cndmask_b32_e32 v84, v229, v84, vcc
	v_cmp_le_i32_e32 vcc, v3, v167
	v_add_u32_e32 v3, 9, v0
	s_nop 0
	v_cndmask_b32_e32 v100, v229, v100, vcc
	v_cmp_le_i32_e32 vcc, v3, v167
	v_add_u32_e32 v3, 41, v0
	s_nop 0
	v_cndmask_b32_e32 v85, v229, v85, vcc
	v_cmp_le_i32_e32 vcc, v3, v167
	v_add_u32_e32 v3, 10, v0
	s_nop 0
	v_cndmask_b32_e32 v101, v229, v101, vcc
	v_cmp_le_i32_e32 vcc, v3, v167
	v_add_u32_e32 v3, 42, v0
	s_nop 0
	v_cndmask_b32_e32 v86, v229, v86, vcc
	v_cmp_le_i32_e32 vcc, v3, v167
	v_add_u32_e32 v3, 11, v0
	s_nop 0
	v_cndmask_b32_e32 v102, v229, v102, vcc
	v_cmp_le_i32_e32 vcc, v3, v167
	v_add_u32_e32 v3, 43, v0
	s_nop 0
	v_cndmask_b32_e32 v87, v229, v87, vcc
	v_cmp_le_i32_e32 vcc, v3, v167
	v_add_u32_e32 v3, 16, v0
	s_nop 0
	v_cndmask_b32_e32 v103, v229, v103, vcc
	v_cmp_le_i32_e32 vcc, v3, v167
	v_add_u32_e32 v3, 48, v0
	s_nop 0
	v_cndmask_b32_e32 v88, v229, v88, vcc
	v_cmp_le_i32_e32 vcc, v3, v167
	v_add_u32_e32 v3, 17, v0
	s_nop 0
	v_cndmask_b32_e32 v104, v229, v104, vcc
	v_cmp_le_i32_e32 vcc, v3, v167
	v_add_u32_e32 v3, 49, v0
	s_nop 0
	v_cndmask_b32_e32 v89, v229, v89, vcc
	v_cmp_le_i32_e32 vcc, v3, v167
	v_add_u32_e32 v3, 18, v0
	s_nop 0
	v_cndmask_b32_e32 v105, v229, v105, vcc
	v_cmp_le_i32_e32 vcc, v3, v167
	v_add_u32_e32 v3, 50, v0
	s_nop 0
	v_cndmask_b32_e32 v90, v229, v90, vcc
	v_cmp_le_i32_e32 vcc, v3, v167
	v_add_u32_e32 v3, 19, v0
	s_nop 0
	v_cndmask_b32_e32 v106, v229, v106, vcc
	v_cmp_le_i32_e32 vcc, v3, v167
	v_add_u32_e32 v3, 51, v0
	s_nop 0
	v_cndmask_b32_e32 v91, v229, v91, vcc
	v_cmp_le_i32_e32 vcc, v3, v167
	v_add_u32_e32 v3, 24, v0
	s_nop 0
	v_cndmask_b32_e32 v107, v229, v107, vcc
	v_cmp_le_i32_e32 vcc, v3, v167
	v_add_u32_e32 v3, 56, v0
	s_nop 0
	v_cndmask_b32_e32 v92, v229, v92, vcc
	v_cmp_le_i32_e32 vcc, v3, v167
	v_add_u32_e32 v3, 25, v0
	s_nop 0
	v_cndmask_b32_e32 v108, v229, v108, vcc
	v_cmp_le_i32_e32 vcc, v3, v167
	v_add_u32_e32 v3, 57, v0
	s_nop 0
	v_cndmask_b32_e32 v93, v229, v93, vcc
	v_cmp_le_i32_e32 vcc, v3, v167
	v_add_u32_e32 v3, 26, v0
	s_nop 0
	v_cndmask_b32_e32 v109, v229, v109, vcc
	v_cmp_le_i32_e32 vcc, v3, v167
	v_add_u32_e32 v3, 58, v0
	s_nop 0
	v_cndmask_b32_e32 v94, v229, v94, vcc
	v_cmp_le_i32_e32 vcc, v3, v167
	v_add_u32_e32 v3, 27, v0
	v_add_u32_e32 v0, 59, v0
	v_cndmask_b32_e32 v110, v229, v110, vcc
	v_cmp_le_i32_e32 vcc, v3, v167
	s_nop 1
	v_cndmask_b32_e32 v95, v229, v95, vcc
	v_cmp_le_i32_e32 vcc, v0, v167
	s_nop 1
	v_cndmask_b32_e32 v111, v229, v111, vcc

; DI unsigned pk2(float lo, float hi) { const f32x2_t v = {lo, hi}; const bf16x2_t b = __builtin_convertvector(v, bf16x2_t); return __builtin_bit_cast(unsigned, b); }
; #define MLA_DMA(t, slot) do { _Pragma("unroll") for (int i_ = 0; i_ < 4; ++i_) { const bf16_t* src_ = (pisk[i_] ? kbase : vbase) + poff[i_] + (size_t)(t) * pstep[i_]; \
;         __builtin_amdgcn_global_load_lds((const unsigned*)src_, (LAS unsigned*)(lds + (slot) * SLOT + (w + 8 * i_) * 1024), 16, 0, 0); } } while (0)
; DI void mla_attn_phase(LAS unsigned char* lds, const bf16_t* Qg, const bf16_t* Kg, const bf16_t* Vtg, bf16_t* MIX) {
;     ...
;                 if (kt + 2 < NT) MLA_DMA(kt + 2, sl2);
;     ...
;                     const float m_new = fmaxf(m_run, mx), alpha = __builtin_amdgcn_exp2f(m_run - m_new); m_run = m_new;
;                     float sum = 0.f;
; #pragma unroll
;                     for (int i = 0; i < 16; ++i) { s0[i] = __builtin_amdgcn_exp2f(s0[i] - m_new); s1[i] = __builtin_amdgcn_exp2f(s1[i] - m_new); sum += s0[i] + s1[i]; }
;                     l_run = l_run * alpha + sum;
;                     if (__any(alpha != 1.f)) {
; #pragma unroll
;                         for (int mt = 0; mt < 4; ++mt)
; #pragma unroll
;                             for (int i = 0; i < 16; ++i) o[mt][i] *= alpha; }
;                     bf16x8 pf[4];
; #pragma unroll
;                     for (int sp = 0; sp < 2; ++sp) { u32x4 p0, p1;
; #pragma unroll
;                         for (int j = 0; j < 4; ++j) { p0[j] = pk2(s0[8 * sp + 2 * j], s0[8 * sp + 2 * j + 1]); p1[j] = pk2(s1[8 * sp + 2 * j], s1[8 * sp + 2 * j + 1]); }
;                         pf[sp] = __builtin_bit_cast(bf16x8, p0); pf[2 + sp] = __builtin_bit_cast(bf16x8, p1); }
.Lmla_dma:
	s_and_b64 vcc, exec, s[28:29]
	s_cbranch_vccnz .Lmla_nodma
	s_mov_b32 m0, s31
	s_nop 0
	global_load_lds_dwordx4 v[210:211], off
	s_add_i32 m0, s31, 0x2000
	s_nop 0
	global_load_lds_dwordx4 v[212:213], off
	s_add_i32 m0, s31, 0x4000
	s_nop 0
	global_load_lds_dwordx4 v[214:215], off
	s_add_i32 m0, s31, 0x6000
	s_nop 0
	global_load_lds_dwordx4 v[216:217], off
.Lmla_nodma:
	s_cmp_gt_i32 s40, s39
	s_cbranch_scc1 .Lmla_x
	v_sub_f32_e32 v80, v80, v3
	v_sub_f32_e32 v96, v96, v3
	v_exp_f32_e32 v80, v80
	v_exp_f32_e32 v96, v96
	v_sub_f32_e32 v81, v81, v3
	v_sub_f32_e32 v97, v97, v3
	v_exp_f32_e32 v81, v81
	v_exp_f32_e32 v97, v97
	v_sub_f32_e32 v82, v82, v3
	v_sub_f32_e32 v98, v98, v3
	v_exp_f32_e32 v82, v82
	v_exp_f32_e32 v98, v98
	v_sub_f32_e32 v83, v83, v3
	v_sub_f32_e32 v99, v99, v3
	v_exp_f32_e32 v83, v83
	v_exp_f32_e32 v99, v99
	v_add_f32_e32 v218, v80, v96
	v_sub_f32_e32 v84, v84, v3
	v_add_f32_e32 v218, 0, v218
	v_add_f32_e32 v219, v81, v97
	v_exp_f32_e32 v226, v84
	v_sub_f32_e32 v84, v100, v3
	v_add_f32_e32 v218, v219, v218
	v_add_f32_e32 v219, v82, v98
	v_exp_f32_e32 v100, v84
	v_sub_f32_e32 v84, v85, v3
	v_add_f32_e32 v218, v219, v218
	v_add_f32_e32 v219, v83, v99
	v_exp_f32_e32 v227, v84
	v_sub_f32_e32 v84, v101, v3
	v_sub_f32_e32 v86, v86, v3
	v_exp_f32_e32 v101, v84
	v_add_f32_e32 v84, v219, v218
	v_exp_f32_e32 v218, v86
	v_sub_f32_e32 v86, v102, v3
	v_exp_f32_e32 v102, v86
	v_sub_f32_e32 v86, v87, v3
	v_exp_f32_e32 v87, v86
	v_sub_f32_e32 v86, v103, v3
	v_exp_f32_e32 v103, v86
	v_sub_f32_e32 v86, v88, v3
	v_exp_f32_e32 v88, v86
	v_sub_f32_e32 v86, v104, v3
	v_exp_f32_e32 v104, v86
	v_sub_f32_e32 v86, v89, v3
	v_exp_f32_e32 v89, v86
	v_sub_f32_e32 v86, v105, v3
	v_exp_f32_e32 v105, v86
	v_sub_f32_e32 v86, v90, v3
	v_exp_f32_e32 v90, v86
	v_sub_f32_e32 v86, v106, v3
	v_exp_f32_e32 v106, v86
	v_sub_f32_e32 v86, v91, v3
	v_exp_f32_e32 v91, v86
	v_sub_f32_e32 v86, v107, v3
	v_exp_f32_e32 v107, v86
	v_sub_f32_e32 v86, v92, v3
	v_add_f32_e32 v85, v226, v100
	v_exp_f32_e32 v219, v86
	v_sub_f32_e32 v86, v108, v3
	v_add_f32_e32 v84, v85, v84
	v_add_f32_e32 v85, v227, v101
	v_exp_f32_e32 v108, v86
	v_sub_f32_e32 v86, v93, v3
	v_add_f32_e32 v84, v85, v84
	v_add_f32_e32 v85, v218, v102
	v_exp_f32_e32 v234, v86
	v_sub_f32_e32 v86, v109, v3
	v_add_f32_e32 v84, v85, v84
	v_add_f32_e32 v85, v87, v103
	v_exp_f32_e32 v109, v86
	v_sub_f32_e32 v86, v94, v3
	v_add_f32_e32 v84, v85, v84
	v_add_f32_e32 v85, v88, v104
	v_exp_f32_e32 v235, v86
	v_sub_f32_e32 v86, v110, v3
	v_add_f32_e32 v84, v85, v84
	v_add_f32_e32 v85, v89, v105
	v_exp_f32_e32 v110, v86
	v_sub_f32_e32 v86, v95, v3
	v_add_f32_e32 v84, v85, v84
	v_add_f32_e32 v85, v90, v106
	v_exp_f32_e32 v95, v86
	v_sub_f32_e32 v86, v111, v3
	v_add_f32_e32 v84, v85, v84
	v_add_f32_e32 v85, v91, v107
	v_exp_f32_e32 v111, v86
	v_add_f32_e32 v84, v85, v84
	v_add_f32_e32 v85, v219, v108
	v_add_f32_e32 v84, v85, v84
	v_add_f32_e32 v85, v234, v109
	v_add_f32_e32 v84, v85, v84
	v_add_f32_e32 v85, v235, v110
	v_add_f32_e32 v84, v85, v84
	v_add_f32_e32 v85, v95, v111
	v_add_f32_e32 v236, v85, v84
	v_fmac_f32_e32 v236, v233, v0
	v_cvt_pk_bf16_f32 v80, v80, v81
	v_cvt_pk_bf16_f32 v84, v96, v97
	v_cvt_pk_bf16_f32 v81, v82, v83
	v_cvt_pk_bf16_f32 v85, v98, v99
	v_cvt_pk_bf16_f32 v82, v226, v227
	v_cvt_pk_bf16_f32 v86, v100, v101
	v_cvt_pk_bf16_f32 v83, v218, v87
	v_cvt_pk_bf16_f32 v87, v102, v103
	v_cvt_pk_bf16_f32 v88, v88, v89
	v_cvt_pk_bf16_f32 v92, v104, v105
	v_cvt_pk_bf16_f32 v89, v90, v91
	v_cvt_pk_bf16_f32 v93, v106, v107
	v_cvt_pk_bf16_f32 v90, v219, v234
	v_cvt_pk_bf16_f32 v94, v108, v109
	v_cvt_pk_bf16_f32 v91, v235, v95
	v_cvt_pk_bf16_f32 v95, v110, v111
.Lmla_x:
	s_cmp_lt_u32 s34, 0x80
	s_cbranch_scc0 .Lmla_xb
	s_add_i32 s30, s42, 2
	s_cmp_ge_i32 s30, s38
	s_cbranch_scc1 .Lmla_xw0
	s_waitcnt vmcnt(4)
	s_branch .Lmla_xb

; DI void mla_attn_phase(LAS unsigned char* lds, const bf16_t* Qg, const bf16_t* Kg, const bf16_t* Vtg, bf16_t* MIX) {
;     ...
;                 __builtin_amdgcn_s_barrier(); asm volatile("" ::: "memory");
;                 sl = sl == 2 ? 0 : sl + 1;
.Lmla_xb:
	s_barrier
	s_cmp_gt_i32 s40, s39
	s_cbranch_scc1 .LBB0_367
	s_waitcnt lgkmcnt(6)
	v_mfma_f32_32x32x16_bf16 v[64:79], v[144:147], v[80:83], v[64:79]
	v_mfma_f32_32x32x16_bf16 v[48:63], v[140:143], v[80:83], v[48:63]
	s_waitcnt lgkmcnt(0)
	v_mfma_f32_32x32x16_bf16 v[32:47], v[148:151], v[80:83], v[32:47]
	v_mfma_f32_32x32x16_bf16 v[16:31], v[152:155], v[80:83], v[16:31]
	ds_read_b128 v[80:83], v1 offset:13376
	ds_read_b128 v[96:99], v1 offset:17984
	ds_read_b128 v[100:103], v1 offset:22592
	ds_read_b128 v[104:107], v1 offset:27200
	v_mfma_f32_32x32x16_bf16 v[64:79], v[136:139], v[88:91], v[64:79]
	v_mfma_f32_32x32x16_bf16 v[48:63], v[12:15], v[88:91], v[48:63]
	v_mfma_f32_32x32x16_bf16 v[32:47], v[4:7], v[88:91], v[32:47]
	v_mfma_f32_32x32x16_bf16 v[16:31], v[8:11], v[88:91], v[16:31]
	ds_read_b128 v[4:7], v1 offset:13408
	ds_read_b128 v[8:11], v1 offset:18016
	ds_read_b128 v[12:15], v1 offset:22624
	ds_read_b128 v[88:91], v1 offset:27232
	s_waitcnt lgkmcnt(4)
	v_mfma_f32_32x32x16_bf16 v[64:79], v[80:83], v[84:87], v[64:79]
	v_mov_b32_e32 v233, v236
	v_mfma_f32_32x32x16_bf16 v[48:63], v[96:99], v[84:87], v[48:63]
	v_mfma_f32_32x32x16_bf16 v[32:47], v[100:103], v[84:87], v[32:47]
	v_mfma_f32_32x32x16_bf16 v[16:31], v[104:107], v[84:87], v[16:31]
	s_waitcnt lgkmcnt(0)
	v_mfma_f32_32x32x16_bf16 v[64:79], v[4:7], v[92:95], v[64:79]
	v_mfma_f32_32x32x16_bf16 v[48:63], v[8:11], v[92:95], v[48:63]
	v_mfma_f32_32x32x16_bf16 v[32:47], v[12:15], v[92:95], v[32:47]
	v_mfma_f32_32x32x16_bf16 v[16:31], v[88:91], v[92:95], v[16:31]
	s_branch .LBB0_371
.LBB0_367:
	v_mov_b32_e32 v3, v234
.LBB0_371:
	s_add_i32 s41, s41, 1
	s_and_b32 s41, s41, 3
	s_add_i32 s42, s42, 1
	s_add_i32 s40, s40, 64
	v_lshl_add_u64 v[216:217], v[216:217], 0, s[18:19]
	v_lshl_add_u64 v[214:215], v[214:215], 0, s[20:21]
	v_lshl_add_u64 v[212:213], v[212:213], 0, s[2:3]
	s_cmp_eq_u32 s38, s42
	v_lshl_add_u64 v[210:211], v[210:211], 0, s[22:23]
	s_cbranch_scc1 .Lmla_exit
	v_mov_b32_e32 v234, v3
	s_branch .LBB0_359
.Lmla_exit:
	s_cmp_lt_u32 s34, 0x80
	s_cbranch_scc0 .LBB0_356
	s_barrier
	s_branch .LBB0_356
